# P3 final and P4 epilogues also use plain write-back stores
# baseline (speedup 1.0000x reference)
.LBB0_619:
	s_cmp_gt_i32 s73, 1
	s_cselect_b64 s[60:61], -1, 0
	s_mov_b64 s[62:63], -1
	s_and_b64 vcc, exec, s[60:61]
	s_mul_i32 s47, s75, 12
	s_cbranch_vccz .LBB0_622
	s_add_i32 s62, s74, s47
	s_add_i32 s62, s62, 8
	s_ashr_i32 s63, s62, 31
	s_lshl_b64 s[62:63], s[62:63], 17
	s_add_u32 s62, s62, 0x1000
	s_addc_u32 s63, s63, 0
	v_lshl_add_u64 v[158:159], v[148:149], 0, s[62:63]
	s_mov_b64 s[62:63], 0x2000
	global_load_dwordx4 v[164:167], v[158:159], off offset:-4096
	global_load_dwordx4 v[168:171], v[158:159], off offset:-3072
	global_load_dwordx4 v[172:175], v[158:159], off offset:-2048
	global_load_dwordx4 v[176:179], v[158:159], off offset:-1024
	global_load_dwordx4 v[180:183], v[158:159], off
	global_load_dwordx4 v[184:187], v[158:159], off offset:1024
	global_load_dwordx4 v[188:191], v[158:159], off offset:2048
	global_load_dwordx4 v[192:195], v[158:159], off offset:3072
	v_lshl_add_u64 v[158:159], v[158:159], 0, s[62:63]
	v_lshl_add_u32 v132, s75, 8, v160
	v_lshl_or_b32 v2, s74, 8, v162
	v_ashrrev_i32_e32 v133, 31, v132
	v_ashrrev_i32_e32 v3, 31, v2
	v_lshlrev_b64 v[132:133], 11, v[132:133]
	v_lshlrev_b64 v[134:135], 1, v[2:3]
	v_lshl_add_u64 v[2:3], s[28:29], 0, v[132:133]
	v_lshl_add_u64 v[2:3], v[2:3], 0, v[134:135]
	global_load_dwordx4 v[206:209], v[158:159], off offset:-4096
	global_load_dwordx4 v[210:213], v[158:159], off offset:-3072
	global_load_dwordx4 v[214:217], v[158:159], off offset:-2048
	global_load_dwordx4 v[218:221], v[158:159], off offset:-1024
	global_load_dwordx4 v[154:157], v[158:159], off
	global_load_dwordx4 v[232:235], v[158:159], off offset:1024
	s_mov_b64 s[62:63], 0x8000
	s_mov_b64 s[64:65], 0x28000
	s_waitcnt vmcnt(13)
	v_lshlrev_b32_e32 v132, 16, v164
	v_and_b32_e32 v133, 0xffff0000, v164
	v_lshlrev_b32_e32 v134, 16, v165
	v_and_b32_e32 v135, 0xffff0000, v165
	v_rcp_f32_e32 v132, v132
	v_rcp_f32_e32 v133, v133
	v_rcp_f32_e32 v134, v134
	v_rcp_f32_e32 v135, v135
	v_pk_mul_f32 v[132:133], v[128:129], v[132:133]
	v_pk_mul_f32 v[134:135], v[130:131], v[134:135]
	v_cvt_pk_bf16_f32 v136, v132, v133
	v_cvt_pk_bf16_f32 v137, v134, v135
	v_lshlrev_b32_e32 v132, 16, v166
	v_and_b32_e32 v133, 0xffff0000, v166
	v_lshlrev_b32_e32 v134, 16, v167
	v_and_b32_e32 v135, 0xffff0000, v167
	v_rcp_f32_e32 v132, v132
	v_rcp_f32_e32 v133, v133
	v_rcp_f32_e32 v134, v134
	v_rcp_f32_e32 v135, v135
	v_pk_mul_f32 v[132:133], v[124:125], v[132:133]
	v_pk_mul_f32 v[134:135], v[126:127], v[134:135]
	v_cvt_pk_bf16_f32 v138, v132, v133
	v_cvt_pk_bf16_f32 v139, v134, v135
	global_store_dwordx4 v[2:3], v[136:139], off
	global_load_dwordx4 v[164:167], v[158:159], off offset:2048
	s_waitcnt vmcnt(14)
	v_lshlrev_b32_e32 v132, 16, v168
	v_and_b32_e32 v133, 0xffff0000, v168
	v_lshlrev_b32_e32 v134, 16, v169
	v_and_b32_e32 v135, 0xffff0000, v169
	v_rcp_f32_e32 v132, v132
	v_rcp_f32_e32 v133, v133
	v_rcp_f32_e32 v134, v134
	v_rcp_f32_e32 v135, v135
	v_pk_mul_f32 v[132:133], v[96:97], v[132:133]
	v_pk_mul_f32 v[134:135], v[98:99], v[134:135]
	v_cvt_pk_bf16_f32 v136, v132, v133
	v_cvt_pk_bf16_f32 v137, v134, v135
	v_lshlrev_b32_e32 v132, 16, v170
	v_and_b32_e32 v133, 0xffff0000, v170
	v_lshlrev_b32_e32 v134, 16, v171
	v_and_b32_e32 v135, 0xffff0000, v171
	v_rcp_f32_e32 v132, v132
	v_rcp_f32_e32 v133, v133
	v_rcp_f32_e32 v134, v134
	v_rcp_f32_e32 v135, v135
	v_pk_mul_f32 v[132:133], v[92:93], v[132:133]
	v_pk_mul_f32 v[134:135], v[94:95], v[134:135]
	v_cvt_pk_bf16_f32 v138, v132, v133
	v_cvt_pk_bf16_f32 v139, v134, v135
	global_store_dwordx4 v[2:3], v[136:139], off offset:256
	v_lshl_add_u64 v[2:3], v[2:3], 0, s[62:63]
	global_load_dwordx4 v[168:171], v[158:159], off offset:3072
	s_waitcnt vmcnt(15)
	v_lshlrev_b32_e32 v132, 16, v172
	v_and_b32_e32 v133, 0xffff0000, v172
	v_lshlrev_b32_e32 v134, 16, v173
	v_and_b32_e32 v135, 0xffff0000, v173
	v_rcp_f32_e32 v132, v132
	v_rcp_f32_e32 v133, v133
	v_rcp_f32_e32 v134, v134
	v_rcp_f32_e32 v135, v135
	v_pk_mul_f32 v[132:133], v[120:121], v[132:133]
	v_pk_mul_f32 v[134:135], v[122:123], v[134:135]
	v_cvt_pk_bf16_f32 v136, v132, v133
	v_cvt_pk_bf16_f32 v137, v134, v135
	v_lshlrev_b32_e32 v132, 16, v174
	v_and_b32_e32 v133, 0xffff0000, v174
	v_lshlrev_b32_e32 v134, 16, v175
	v_and_b32_e32 v135, 0xffff0000, v175
	v_rcp_f32_e32 v132, v132
	v_rcp_f32_e32 v133, v133
	v_rcp_f32_e32 v134, v134
	v_rcp_f32_e32 v135, v135
	v_pk_mul_f32 v[132:133], v[116:117], v[132:133]
	v_pk_mul_f32 v[134:135], v[118:119], v[134:135]
	v_cvt_pk_bf16_f32 v138, v132, v133
	v_cvt_pk_bf16_f32 v139, v134, v135
	global_store_dwordx4 v[2:3], v[136:139], off
	s_waitcnt vmcnt(15)
	v_lshlrev_b32_e32 v132, 16, v176
	v_and_b32_e32 v133, 0xffff0000, v176
	v_lshlrev_b32_e32 v134, 16, v177
	v_and_b32_e32 v135, 0xffff0000, v177
	v_rcp_f32_e32 v132, v132
	v_rcp_f32_e32 v133, v133
	v_rcp_f32_e32 v134, v134
	v_rcp_f32_e32 v135, v135
	v_pk_mul_f32 v[132:133], v[88:89], v[132:133]
	v_pk_mul_f32 v[134:135], v[90:91], v[134:135]
	v_cvt_pk_bf16_f32 v136, v132, v133
	v_cvt_pk_bf16_f32 v137, v134, v135
	v_lshlrev_b32_e32 v132, 16, v178
	v_and_b32_e32 v133, 0xffff0000, v178
	v_lshlrev_b32_e32 v134, 16, v179
	v_and_b32_e32 v135, 0xffff0000, v179
	v_rcp_f32_e32 v132, v132
	v_rcp_f32_e32 v133, v133
	v_rcp_f32_e32 v134, v134
	v_rcp_f32_e32 v135, v135
	v_pk_mul_f32 v[132:133], v[84:85], v[132:133]
	v_pk_mul_f32 v[134:135], v[86:87], v[134:135]
	v_cvt_pk_bf16_f32 v138, v132, v133
	v_cvt_pk_bf16_f32 v139, v134, v135
	global_store_dwordx4 v[2:3], v[136:139], off offset:256
	v_lshl_add_u64 v[2:3], v[2:3], 0, s[62:63]
	s_waitcnt vmcnt(15)
	v_lshlrev_b32_e32 v132, 16, v180
	v_and_b32_e32 v133, 0xffff0000, v180
	v_lshlrev_b32_e32 v134, 16, v181
	v_and_b32_e32 v135, 0xffff0000, v181
	v_rcp_f32_e32 v132, v132
	v_rcp_f32_e32 v133, v133
	v_rcp_f32_e32 v134, v134
	v_rcp_f32_e32 v135, v135
	v_pk_mul_f32 v[132:133], v[112:113], v[132:133]
	v_pk_mul_f32 v[134:135], v[114:115], v[134:135]
	v_cvt_pk_bf16_f32 v136, v132, v133
	v_cvt_pk_bf16_f32 v137, v134, v135
	v_lshlrev_b32_e32 v132, 16, v182
	v_and_b32_e32 v133, 0xffff0000, v182
	v_lshlrev_b32_e32 v134, 16, v183
	v_and_b32_e32 v135, 0xffff0000, v183
	v_rcp_f32_e32 v132, v132
	v_rcp_f32_e32 v133, v133
	v_rcp_f32_e32 v134, v134
	v_rcp_f32_e32 v135, v135
	v_pk_mul_f32 v[132:133], v[108:109], v[132:133]
	v_pk_mul_f32 v[134:135], v[110:111], v[134:135]
	v_cvt_pk_bf16_f32 v138, v132, v133
	v_cvt_pk_bf16_f32 v139, v134, v135
	global_store_dwordx4 v[2:3], v[136:139], off
	s_waitcnt vmcnt(15)
	v_lshlrev_b32_e32 v132, 16, v184
	v_and_b32_e32 v133, 0xffff0000, v184
	v_lshlrev_b32_e32 v134, 16, v185
	v_and_b32_e32 v135, 0xffff0000, v185
	v_rcp_f32_e32 v132, v132
	v_rcp_f32_e32 v133, v133
	v_rcp_f32_e32 v134, v134
	v_rcp_f32_e32 v135, v135
	v_pk_mul_f32 v[132:133], v[80:81], v[132:133]
	v_pk_mul_f32 v[134:135], v[82:83], v[134:135]
	v_cvt_pk_bf16_f32 v136, v132, v133
	v_cvt_pk_bf16_f32 v137, v134, v135
	v_lshlrev_b32_e32 v132, 16, v186
	v_and_b32_e32 v133, 0xffff0000, v186
	v_lshlrev_b32_e32 v134, 16, v187
	v_and_b32_e32 v135, 0xffff0000, v187
	v_rcp_f32_e32 v132, v132
	v_rcp_f32_e32 v133, v133
	v_rcp_f32_e32 v134, v134
	v_rcp_f32_e32 v135, v135
	v_pk_mul_f32 v[132:133], v[76:77], v[132:133]
	v_pk_mul_f32 v[134:135], v[78:79], v[134:135]
	v_cvt_pk_bf16_f32 v138, v132, v133
	v_cvt_pk_bf16_f32 v139, v134, v135
	global_store_dwordx4 v[2:3], v[136:139], off offset:256
	v_lshl_add_u64 v[2:3], v[2:3], 0, s[62:63]
	s_waitcnt vmcnt(15)
	v_lshlrev_b32_e32 v132, 16, v188
	v_and_b32_e32 v133, 0xffff0000, v188
	v_lshlrev_b32_e32 v134, 16, v189
	v_and_b32_e32 v135, 0xffff0000, v189
	v_rcp_f32_e32 v132, v132
	v_rcp_f32_e32 v133, v133
	v_rcp_f32_e32 v134, v134
	v_rcp_f32_e32 v135, v135
	v_pk_mul_f32 v[132:133], v[104:105], v[132:133]
	v_pk_mul_f32 v[134:135], v[106:107], v[134:135]
	v_cvt_pk_bf16_f32 v136, v132, v133
	v_cvt_pk_bf16_f32 v137, v134, v135
	v_lshlrev_b32_e32 v132, 16, v190
	v_and_b32_e32 v133, 0xffff0000, v190
	v_lshlrev_b32_e32 v134, 16, v191
	v_and_b32_e32 v135, 0xffff0000, v191
	v_rcp_f32_e32 v132, v132
	v_rcp_f32_e32 v133, v133
	v_rcp_f32_e32 v134, v134
	v_rcp_f32_e32 v135, v135
	v_pk_mul_f32 v[132:133], v[100:101], v[132:133]
	v_pk_mul_f32 v[134:135], v[102:103], v[134:135]
	v_cvt_pk_bf16_f32 v138, v132, v133
	v_cvt_pk_bf16_f32 v139, v134, v135
	global_store_dwordx4 v[2:3], v[136:139], off
	s_waitcnt vmcnt(15)
	v_lshlrev_b32_e32 v132, 16, v192
	v_and_b32_e32 v133, 0xffff0000, v192
	v_lshlrev_b32_e32 v134, 16, v193
	v_and_b32_e32 v135, 0xffff0000, v193
	v_rcp_f32_e32 v132, v132
	v_rcp_f32_e32 v133, v133
	v_rcp_f32_e32 v134, v134
	v_rcp_f32_e32 v135, v135
	v_pk_mul_f32 v[132:133], v[72:73], v[132:133]
	v_pk_mul_f32 v[134:135], v[74:75], v[134:135]
	v_cvt_pk_bf16_f32 v136, v132, v133
	v_cvt_pk_bf16_f32 v137, v134, v135
	v_lshlrev_b32_e32 v132, 16, v194
	v_and_b32_e32 v133, 0xffff0000, v194
	v_lshlrev_b32_e32 v134, 16, v195
	v_and_b32_e32 v135, 0xffff0000, v195
	v_rcp_f32_e32 v132, v132
	v_rcp_f32_e32 v133, v133
	v_rcp_f32_e32 v134, v134
	v_rcp_f32_e32 v135, v135
	v_pk_mul_f32 v[132:133], v[68:69], v[132:133]
	v_pk_mul_f32 v[134:135], v[70:71], v[134:135]
	v_cvt_pk_bf16_f32 v138, v132, v133
	v_cvt_pk_bf16_f32 v139, v134, v135
	global_store_dwordx4 v[2:3], v[136:139], off offset:256
	v_lshl_add_u64 v[2:3], v[2:3], 0, s[64:65]
	s_waitcnt vmcnt(15)
	v_lshlrev_b32_e32 v132, 16, v206
	v_and_b32_e32 v133, 0xffff0000, v206
	v_lshlrev_b32_e32 v134, 16, v207
	v_and_b32_e32 v135, 0xffff0000, v207
	v_rcp_f32_e32 v132, v132
	v_rcp_f32_e32 v133, v133
	v_rcp_f32_e32 v134, v134
	v_rcp_f32_e32 v135, v135
	v_pk_mul_f32 v[132:133], v[64:65], v[132:133]
	v_pk_mul_f32 v[134:135], v[66:67], v[134:135]
	v_cvt_pk_bf16_f32 v136, v132, v133
	v_cvt_pk_bf16_f32 v137, v134, v135
	v_lshlrev_b32_e32 v132, 16, v208
	v_and_b32_e32 v133, 0xffff0000, v208
	v_lshlrev_b32_e32 v134, 16, v209
	v_and_b32_e32 v135, 0xffff0000, v209
	v_rcp_f32_e32 v132, v132
	v_rcp_f32_e32 v133, v133
	v_rcp_f32_e32 v134, v134
	v_rcp_f32_e32 v135, v135
	v_pk_mul_f32 v[132:133], v[60:61], v[132:133]
	v_pk_mul_f32 v[134:135], v[62:63], v[134:135]
	v_cvt_pk_bf16_f32 v138, v132, v133
	v_cvt_pk_bf16_f32 v139, v134, v135
	global_store_dwordx4 v[2:3], v[136:139], off
	s_waitcnt vmcnt(15)
	v_lshlrev_b32_e32 v132, 16, v210
	v_and_b32_e32 v133, 0xffff0000, v210
	v_lshlrev_b32_e32 v134, 16, v211
	v_and_b32_e32 v135, 0xffff0000, v211
	v_rcp_f32_e32 v132, v132
	v_rcp_f32_e32 v133, v133
	v_rcp_f32_e32 v134, v134
	v_rcp_f32_e32 v135, v135
	v_pk_mul_f32 v[132:133], v[32:33], v[132:133]
	v_pk_mul_f32 v[134:135], v[34:35], v[134:135]
	v_cvt_pk_bf16_f32 v136, v132, v133
	v_cvt_pk_bf16_f32 v137, v134, v135
	v_lshlrev_b32_e32 v132, 16, v212
	v_and_b32_e32 v133, 0xffff0000, v212
	v_lshlrev_b32_e32 v134, 16, v213
	v_and_b32_e32 v135, 0xffff0000, v213
	v_rcp_f32_e32 v132, v132
	v_rcp_f32_e32 v133, v133
	v_rcp_f32_e32 v134, v134
	v_rcp_f32_e32 v135, v135
	v_pk_mul_f32 v[132:133], v[28:29], v[132:133]
	v_pk_mul_f32 v[134:135], v[30:31], v[134:135]
	v_cvt_pk_bf16_f32 v138, v132, v133
	v_cvt_pk_bf16_f32 v139, v134, v135
	global_store_dwordx4 v[2:3], v[136:139], off offset:256
	v_lshl_add_u64 v[2:3], v[2:3], 0, s[62:63]
	s_waitcnt vmcnt(15)
	v_lshlrev_b32_e32 v132, 16, v214
	v_and_b32_e32 v133, 0xffff0000, v214
	v_lshlrev_b32_e32 v134, 16, v215
	v_and_b32_e32 v135, 0xffff0000, v215
	v_rcp_f32_e32 v132, v132
	v_rcp_f32_e32 v133, v133
	v_rcp_f32_e32 v134, v134
	v_rcp_f32_e32 v135, v135
	v_pk_mul_f32 v[132:133], v[56:57], v[132:133]
	v_pk_mul_f32 v[134:135], v[58:59], v[134:135]
	v_cvt_pk_bf16_f32 v136, v132, v133
	v_cvt_pk_bf16_f32 v137, v134, v135
	v_lshlrev_b32_e32 v132, 16, v216
	v_and_b32_e32 v133, 0xffff0000, v216
	v_lshlrev_b32_e32 v134, 16, v217
	v_and_b32_e32 v135, 0xffff0000, v217
	v_rcp_f32_e32 v132, v132
	v_rcp_f32_e32 v133, v133
	v_rcp_f32_e32 v134, v134
	v_rcp_f32_e32 v135, v135
	v_pk_mul_f32 v[132:133], v[52:53], v[132:133]
	v_pk_mul_f32 v[134:135], v[54:55], v[134:135]
	v_cvt_pk_bf16_f32 v138, v132, v133
	v_cvt_pk_bf16_f32 v139, v134, v135
	global_store_dwordx4 v[2:3], v[136:139], off
	s_waitcnt vmcnt(15)
	v_lshlrev_b32_e32 v132, 16, v218
	v_and_b32_e32 v133, 0xffff0000, v218
	v_lshlrev_b32_e32 v134, 16, v219
	v_and_b32_e32 v135, 0xffff0000, v219
	v_rcp_f32_e32 v132, v132
	v_rcp_f32_e32 v133, v133
	v_rcp_f32_e32 v134, v134
	v_rcp_f32_e32 v135, v135
	v_pk_mul_f32 v[132:133], v[24:25], v[132:133]
	v_pk_mul_f32 v[134:135], v[26:27], v[134:135]
	v_cvt_pk_bf16_f32 v136, v132, v133
	v_cvt_pk_bf16_f32 v137, v134, v135
	v_lshlrev_b32_e32 v132, 16, v220
	v_and_b32_e32 v133, 0xffff0000, v220
	v_lshlrev_b32_e32 v134, 16, v221
	v_and_b32_e32 v135, 0xffff0000, v221
	v_rcp_f32_e32 v132, v132
	v_rcp_f32_e32 v133, v133
	v_rcp_f32_e32 v134, v134
	v_rcp_f32_e32 v135, v135
	v_pk_mul_f32 v[132:133], v[20:21], v[132:133]
	v_pk_mul_f32 v[134:135], v[22:23], v[134:135]
	v_cvt_pk_bf16_f32 v138, v132, v133
	v_cvt_pk_bf16_f32 v139, v134, v135
	global_store_dwordx4 v[2:3], v[136:139], off offset:256
	v_lshl_add_u64 v[2:3], v[2:3], 0, s[62:63]
	s_waitcnt vmcnt(15)
	v_lshlrev_b32_e32 v132, 16, v154
	v_and_b32_e32 v133, 0xffff0000, v154
	v_lshlrev_b32_e32 v134, 16, v155
	v_and_b32_e32 v135, 0xffff0000, v155
	v_rcp_f32_e32 v132, v132
	v_rcp_f32_e32 v133, v133
	v_rcp_f32_e32 v134, v134
	v_rcp_f32_e32 v135, v135
	v_pk_mul_f32 v[132:133], v[48:49], v[132:133]
	v_pk_mul_f32 v[134:135], v[50:51], v[134:135]
	v_cvt_pk_bf16_f32 v136, v132, v133
	v_cvt_pk_bf16_f32 v137, v134, v135
	v_lshlrev_b32_e32 v132, 16, v156
	v_and_b32_e32 v133, 0xffff0000, v156
	v_lshlrev_b32_e32 v134, 16, v157
	v_and_b32_e32 v135, 0xffff0000, v157
	v_rcp_f32_e32 v132, v132
	v_rcp_f32_e32 v133, v133
	v_rcp_f32_e32 v134, v134
	v_rcp_f32_e32 v135, v135
	v_pk_mul_f32 v[132:133], v[44:45], v[132:133]
	v_pk_mul_f32 v[134:135], v[46:47], v[134:135]
	v_cvt_pk_bf16_f32 v138, v132, v133
	v_cvt_pk_bf16_f32 v139, v134, v135
	global_store_dwordx4 v[2:3], v[136:139], off
	s_waitcnt vmcnt(15)
	v_lshlrev_b32_e32 v132, 16, v232
	v_and_b32_e32 v133, 0xffff0000, v232
	v_lshlrev_b32_e32 v134, 16, v233
	v_and_b32_e32 v135, 0xffff0000, v233
	v_rcp_f32_e32 v132, v132
	v_rcp_f32_e32 v133, v133
	v_rcp_f32_e32 v134, v134
	v_rcp_f32_e32 v135, v135
	v_pk_mul_f32 v[132:133], v[16:17], v[132:133]
	v_pk_mul_f32 v[134:135], v[18:19], v[134:135]
	v_cvt_pk_bf16_f32 v136, v132, v133
	v_cvt_pk_bf16_f32 v137, v134, v135
	v_lshlrev_b32_e32 v132, 16, v234
	v_and_b32_e32 v133, 0xffff0000, v234
	v_lshlrev_b32_e32 v134, 16, v235
	v_and_b32_e32 v135, 0xffff0000, v235
	v_rcp_f32_e32 v132, v132
	v_rcp_f32_e32 v133, v133
	v_rcp_f32_e32 v134, v134
	v_rcp_f32_e32 v135, v135
	v_pk_mul_f32 v[132:133], v[12:13], v[132:133]
	v_pk_mul_f32 v[134:135], v[14:15], v[134:135]
	v_cvt_pk_bf16_f32 v138, v132, v133
	v_cvt_pk_bf16_f32 v139, v134, v135
	global_store_dwordx4 v[2:3], v[136:139], off offset:256
	v_lshl_add_u64 v[2:3], v[2:3], 0, s[62:63]
	s_waitcnt vmcnt(14)
	v_lshlrev_b32_e32 v132, 16, v164
	v_and_b32_e32 v133, 0xffff0000, v164
	v_lshlrev_b32_e32 v134, 16, v165
	v_and_b32_e32 v135, 0xffff0000, v165
	v_rcp_f32_e32 v132, v132
	v_rcp_f32_e32 v133, v133
	v_rcp_f32_e32 v134, v134
	v_rcp_f32_e32 v135, v135
	v_pk_mul_f32 v[132:133], v[40:41], v[132:133]
	v_pk_mul_f32 v[134:135], v[42:43], v[134:135]
	v_cvt_pk_bf16_f32 v136, v132, v133
	v_cvt_pk_bf16_f32 v137, v134, v135
	v_lshlrev_b32_e32 v132, 16, v166
	v_and_b32_e32 v133, 0xffff0000, v166
	v_lshlrev_b32_e32 v134, 16, v167
	v_and_b32_e32 v135, 0xffff0000, v167
	v_rcp_f32_e32 v132, v132
	v_rcp_f32_e32 v133, v133
	v_rcp_f32_e32 v134, v134
	v_rcp_f32_e32 v135, v135
	v_pk_mul_f32 v[132:133], v[36:37], v[132:133]
	v_pk_mul_f32 v[134:135], v[38:39], v[134:135]
	v_cvt_pk_bf16_f32 v138, v132, v133
	v_cvt_pk_bf16_f32 v139, v134, v135
	global_store_dwordx4 v[2:3], v[136:139], off
	s_waitcnt vmcnt(13)
	v_lshlrev_b32_e32 v132, 16, v168
	v_and_b32_e32 v133, 0xffff0000, v168
	v_lshlrev_b32_e32 v134, 16, v169
	v_and_b32_e32 v135, 0xffff0000, v169
	v_rcp_f32_e32 v132, v132
	v_rcp_f32_e32 v133, v133
	v_rcp_f32_e32 v134, v134
	v_rcp_f32_e32 v135, v135
	v_pk_mul_f32 v[132:133], v[8:9], v[132:133]
	v_pk_mul_f32 v[134:135], v[10:11], v[134:135]
	v_cvt_pk_bf16_f32 v136, v132, v133
	v_cvt_pk_bf16_f32 v137, v134, v135
	v_lshlrev_b32_e32 v132, 16, v170
	v_and_b32_e32 v133, 0xffff0000, v170
	v_lshlrev_b32_e32 v134, 16, v171
	v_and_b32_e32 v135, 0xffff0000, v171
	v_rcp_f32_e32 v132, v132
	v_rcp_f32_e32 v133, v133
	v_rcp_f32_e32 v134, v134
	v_rcp_f32_e32 v135, v135
	v_pk_mul_f32 v[132:133], v[4:5], v[132:133]
	v_pk_mul_f32 v[134:135], v[6:7], v[134:135]
	v_cvt_pk_bf16_f32 v138, v132, v133
	v_cvt_pk_bf16_f32 v139, v134, v135
	global_store_dwordx4 v[2:3], v[136:139], off offset:256
	s_cbranch_execz .LBB0_623
